# v41 + L2 warm-up of the residual (HB) tile in the last K-loop trip of P2/P6/P8 (2 dummy dword loads per thread)
# baseline (speedup 1.0000x reference)
; #define PG8_STAGE(bufoff, gbase, voff) do { _Pragma("unroll") for (int _i = 0; _i < 2; ++_i) \
;         __builtin_amdgcn_global_load_lds((const unsigned*)((const char*)(gbase) + (voff)[_i]), (PG8_LAS unsigned*)(lds + (bufoff) + ldsw + _i * 8192), 16, 0, 0); } while (0)
; #define PG8_LDA(dst, b, h) do { _Pragma("unroll") for (int m = 0; m < 4; ++m) _Pragma("unroll") for (int k = 0; k < 2; ++k) dst[m][k] = *(const PG8_LAS bf16x8*)(lds + PG8_SA(b, h) + aoff + m * 2048 + k * 1024); } while (0)
; #define PG8_LDB(dst, b, h) do { _Pragma("unroll") for (int n = 0; n < 2; ++n) _Pragma("unroll") for (int k = 0; k < 2; ++k) dst[n][k] = *(const PG8_LAS bf16x8*)(lds + PG8_SB(b, h) + boff + n * 2048 + k * 1024); } while (0)
; #define PG8_WAIT_V(n) asm volatile("s_waitcnt vmcnt(" #n ")" ::: "memory")
; #define PG8_WAIT_L(n) asm volatile("s_waitcnt lgkmcnt(" #n ")" ::: "memory")
; #define PG8_BAR __builtin_amdgcn_s_barrier()
; #define PG8_SCHED __builtin_amdgcn_sched_barrier(0)
;     __device__ __forceinline__ char* hb_at(const Unit& u, int ai, int m, int bj, int wr, int wc, int fr, int fq) const {
;         return (char*)hb + ((size_t)((u.pm * 16 + u.pn * 4 + bj * 2 + (wc >> 1)) * 2 + ai) * HTB) + lds_byte(wr * 64 + m * 16 + fr, (wc & 1) * 32 + 8 * fq); }
; template <class Epi, class Sched, bool ALIGN_EPI = false, bool SP2 = false>
; __device__ __forceinline__ void gemm_phase(PG8_LAS unsigned char* lds, const Gemm g, const Sched& S, const Epi& E) {
;     ...
;             const bool last = (t == nt - 2);
;             const char* a1 = cA + (size_t)(t + 1) * kstepA;
;             const char* a2 = last ? nA : cA + (size_t)(t + 2) * kstepA; const char* b2 = last ? nB : cB + (size_t)(t + 2) * kstep;
;             const char* a3 = a2 + kstepA; const char* b3 = b2 + kstep;
;             if (last && has_next) S.a_ready(nxt);
;             if constexpr (SP2) {
;             PG8_LDB(B0, 0, 0); PG8_LDB(B1, 0, 1); PG8_SCHED; PG8_LDA(At, 0, 0); PG8_STAGE(PG8_SA(1, 1), a1 + hstepA, voffA);
;             PG8_WAIT_V(8); PG8_WAIT_L(0); PG8_BAR; PG8_MMA(0, 0, At, B0); PG8_MMA(0, 1, At, B1); PG8_BAR; PG8_SCHED;
;             PG8_LDA(At, 0, 1); PG8_STAGE(PG8_SB(0, 0), b2, voffB); PG8_STAGE(PG8_SB(0, 1), b2 + hstepB, voffB); PG8_STAGE(PG8_SA(0, 0), a2, voffA);
;             PG8_WAIT_V(8); PG8_WAIT_L(0); PG8_BAR; PG8_MMA(1, 0, At, B0); PG8_MMA(1, 1, At, B1); PG8_BAR; PG8_SCHED;
.LBB0_226:
	ds_read_b128 v[112:115], v210
	ds_read_b128 v[124:127], v210 offset:1024
	ds_read_b128 v[136:139], v210 offset:2048
	ds_read_b128 v[140:143], v210 offset:3072
	ds_read_b128 v[144:147], v211
	ds_read_b128 v[148:151], v211 offset:1024
	ds_read_b128 v[152:155], v211 offset:2048
	ds_read_b128 v[156:159], v211 offset:3072
	s_cmp_eq_u32 s73, 40
	s_cselect_b32 s9, s1, s69
	s_cselect_b32 s8, s0, s68
	s_cselect_b32 s75, s63, s71
	s_cselect_b32 s74, s62, s70
	s_cmp_eq_u32 s73, 40
	s_cbranch_scc0 .Lhbpf_skip_1
	s_lshl_b32 s98, s76, 5
	s_lshl_b32 s99, s72, 3
	s_add_i32 s98, s98, s99
	s_mov_b32 s99, 0
	s_lshl_b64 s[98:99], s[98:99], 14
	s_add_u32 s98, s98, s22
	s_addc_u32 s99, s99, s23
	s_add_u32 s98, s98, 0x3000000
	s_addc_u32 s99, s99, 0
	v_readlane_b32 s100, v246, 6
	v_mbcnt_lo_u32_b32 v247, -1, 0
	v_mbcnt_hi_u32_b32 v247, -1, v247
	s_nop 1
	v_lshl_add_u32 v247, s100, 6, v247
	v_lshlrev_b32_e32 v247, 7, v247
	v_add_u32_e32 v249, 0x10000, v247
	s_nop 0
	global_load_dword v248, v247, s[98:99]
	global_load_dword v248, v249, s[98:99]
.Lhbpf_skip_1:
	v_lshl_add_u64 v[208:209], s[68:69], 0, v[184:185]
	v_lshl_add_u64 v[216:217], v[208:209], 0, s[96:97]
	s_add_i32 m0, s15, 0xc000
	ds_read_b128 v[160:163], v212
	ds_read_b128 v[164:167], v212 offset:1024
	ds_read_b128 v[168:171], v212 offset:2048
	ds_read_b128 v[172:175], v212 offset:3072
	ds_read_b128 v[176:179], v212 offset:4096
	ds_read_b128 v[180:183], v212 offset:5120
	ds_read_b128 v[220:223], v212 offset:6144
	ds_read_b128 v[224:227], v212 offset:7168
	global_load_lds_dwordx4 v[216:217], off
	v_lshl_add_u64 v[208:209], v[208:209], 0, s[60:61]
	s_add_i32 m0, s15, 0xe000
	s_nop 0
	global_load_lds_dwordx4 v[208:209], off
	s_waitcnt vmcnt(8)
	s_waitcnt lgkmcnt(0)
	s_barrier
	s_waitcnt lgkmcnt(0)
	v_mfma_f32_16x16x32_bf16 v[132:135], v[112:115], v[160:163], v[132:135]
	v_mfma_f32_16x16x32_bf16 v[128:131], v[136:139], v[160:163], v[128:131]
	v_mfma_f32_16x16x32_bf16 v[108:111], v[112:115], v[168:171], v[108:111]
	v_mfma_f32_16x16x32_bf16 v[104:107], v[136:139], v[168:171], v[104:107]
	v_mfma_f32_16x16x32_bf16 v[92:95], v[112:115], v[176:179], v[92:95]
	v_mfma_f32_16x16x32_bf16 v[88:91], v[136:139], v[176:179], v[88:91]
	v_mfma_f32_16x16x32_bf16 v[76:79], v[112:115], v[220:223], v[76:79]
	v_mfma_f32_16x16x32_bf16 v[72:75], v[136:139], v[220:223], v[72:75]
	v_mfma_f32_16x16x32_bf16 v[132:135], v[124:127], v[164:167], v[132:135]
	v_mfma_f32_16x16x32_bf16 v[128:131], v[140:143], v[164:167], v[128:131]
	v_mfma_f32_16x16x32_bf16 v[108:111], v[124:127], v[172:175], v[108:111]
	v_mfma_f32_16x16x32_bf16 v[104:107], v[140:143], v[172:175], v[104:107]
	v_mfma_f32_16x16x32_bf16 v[92:95], v[124:127], v[180:183], v[92:95]
	v_mfma_f32_16x16x32_bf16 v[88:91], v[140:143], v[180:183], v[88:91]
	v_mfma_f32_16x16x32_bf16 v[76:79], v[124:127], v[224:227], v[76:79]
	v_mfma_f32_16x16x32_bf16 v[72:75], v[140:143], v[224:227], v[72:75]
	v_mfma_f32_16x16x32_bf16 v[120:123], v[144:147], v[160:163], v[120:123]
	v_mfma_f32_16x16x32_bf16 v[116:119], v[152:155], v[160:163], v[116:119]
	v_mfma_f32_16x16x32_bf16 v[100:103], v[144:147], v[168:171], v[100:103]
	v_mfma_f32_16x16x32_bf16 v[96:99], v[152:155], v[168:171], v[96:99]
	v_mfma_f32_16x16x32_bf16 v[84:87], v[144:147], v[176:179], v[84:87]
	v_mfma_f32_16x16x32_bf16 v[80:83], v[152:155], v[176:179], v[80:83]
	v_mfma_f32_16x16x32_bf16 v[68:71], v[144:147], v[220:223], v[68:71]
	v_mfma_f32_16x16x32_bf16 v[64:67], v[152:155], v[220:223], v[64:67]
	v_mfma_f32_16x16x32_bf16 v[120:123], v[148:151], v[164:167], v[120:123]
	v_mfma_f32_16x16x32_bf16 v[116:119], v[156:159], v[164:167], v[116:119]
	v_mfma_f32_16x16x32_bf16 v[100:103], v[148:151], v[172:175], v[100:103]
	v_mfma_f32_16x16x32_bf16 v[96:99], v[156:159], v[172:175], v[96:99]
	v_mfma_f32_16x16x32_bf16 v[84:87], v[148:151], v[180:183], v[84:87]
	v_mfma_f32_16x16x32_bf16 v[80:83], v[156:159], v[180:183], v[80:83]
	v_mfma_f32_16x16x32_bf16 v[68:71], v[148:151], v[224:227], v[68:71]
	v_mfma_f32_16x16x32_bf16 v[64:67], v[156:159], v[224:227], v[64:67]
	s_barrier
	s_add_i32 s33, s89, s14
	v_lshl_add_u64 v[208:209], s[74:75], 0, v[184:185]
	s_mov_b32 m0, s33
	ds_read_b128 v[160:163], v212 offset:16384
	ds_read_b128 v[164:167], v212 offset:17408
	ds_read_b128 v[168:171], v212 offset:18432
	ds_read_b128 v[172:175], v212 offset:19456
	ds_read_b128 v[176:179], v212 offset:20480
	ds_read_b128 v[180:183], v212 offset:21504
	ds_read_b128 v[220:223], v212 offset:22528
	ds_read_b128 v[224:227], v212 offset:23552
	global_load_lds_dwordx4 v[208:209], off
	v_lshl_add_u64 v[216:217], v[208:209], 0, s[30:31]
	s_add_i32 m0, s33, 0x2000
	s_add_i32 s33, s90, s14
	global_load_lds_dwordx4 v[216:217], off
	v_lshl_add_u64 v[216:217], v[208:209], 0, s[34:35]
	s_mov_b32 m0, s33
	s_nop 0
	global_load_lds_dwordx4 v[216:217], off
	v_lshl_add_u64 v[216:217], v[208:209], 0, s[36:37]
	s_add_i32 m0, s33, 0x2000
	s_nop 0
	global_load_lds_dwordx4 v[216:217], off
	v_lshl_add_u64 v[216:217], s[8:9], 0, v[184:185]
	s_mov_b32 m0, s15
	v_lshl_add_u64 v[228:229], v[216:217], 0, s[30:31]
	global_load_lds_dwordx4 v[216:217], off
	s_mov_b32 m0, s17
	s_nop 0
	global_load_lds_dwordx4 v[228:229], off
	s_waitcnt vmcnt(8)
	s_waitcnt lgkmcnt(0)
	s_barrier
; #define PG8_STAGE(bufoff, gbase, voff) do { _Pragma("unroll") for (int _i = 0; _i < 2; ++_i) \
;         __builtin_amdgcn_global_load_lds((const unsigned*)((const char*)(gbase) + (voff)[_i]), (PG8_LAS unsigned*)(lds + (bufoff) + ldsw + _i * 8192), 16, 0, 0); } while (0)
; #define PG8_LDA(dst, b, h) do { _Pragma("unroll") for (int m = 0; m < 4; ++m) _Pragma("unroll") for (int k = 0; k < 2; ++k) dst[m][k] = *(const PG8_LAS bf16x8*)(lds + PG8_SA(b, h) + aoff + m * 2048 + k * 1024); } while (0)
; #define PG8_LDB(dst, b, h) do { _Pragma("unroll") for (int n = 0; n < 2; ++n) _Pragma("unroll") for (int k = 0; k < 2; ++k) dst[n][k] = *(const PG8_LAS bf16x8*)(lds + PG8_SB(b, h) + boff + n * 2048 + k * 1024); } while (0)
; #define PG8_MMA(ai, bj, At, Bt) do { __builtin_amdgcn_s_setprio(1); _Pragma("unroll") for (int m = 0; m < 4; ++m) _Pragma("unroll") for (int n = 0; n < 2; ++n) _Pragma("unroll") for (int k = 0; k < 2; ++k) \
;         acc[ai][bj][m][n] = __builtin_amdgcn_mfma_f32_16x16x32_bf16(Bt[n][k], At[m][k], acc[ai][bj][m][n], 0, 0, 0); __builtin_amdgcn_s_setprio(0); } while (0)
; #define PG8_WAIT_V(n) asm volatile("s_waitcnt vmcnt(" #n ")" ::: "memory")
; #define PG8_WAIT_L(n) asm volatile("s_waitcnt lgkmcnt(" #n ")" ::: "memory")
; #define PG8_BAR __builtin_amdgcn_s_barrier()
; #define PG8_SCHED __builtin_amdgcn_sched_barrier(0)
; template <class Epi, class Sched, bool ALIGN_EPI = false, bool SP2 = false>
; __device__ __forceinline__ void gemm_phase(PG8_LAS unsigned char* lds, const Gemm g, const Sched& S, const Epi& E) {
;     ...
;             PG8_WAIT_V(8); PG8_WAIT_L(0); PG8_BAR; PG8_MMA(1, 0, At, B0); PG8_MMA(1, 1, At, B1); PG8_BAR; PG8_SCHED;
;             PG8_LDB(B0, 1, 0); PG8_LDB(B1, 1, 1); PG8_SCHED; PG8_LDA(At, 1, 0); PG8_STAGE(PG8_SA(0, 1), a2 + hstepA, voffA);
;             PG8_WAIT_V(8); PG8_WAIT_L(0); PG8_BAR; PG8_MMA(0, 0, At, B0); PG8_MMA(0, 1, At, B1); PG8_BAR; PG8_SCHED;
	s_waitcnt lgkmcnt(0)
	v_mfma_f32_16x16x32_bf16 v[60:63], v[112:115], v[160:163], v[60:63]
	v_mfma_f32_16x16x32_bf16 v[56:59], v[136:139], v[160:163], v[56:59]
	v_mfma_f32_16x16x32_bf16 v[44:47], v[112:115], v[168:171], v[44:47]
	v_mfma_f32_16x16x32_bf16 v[40:43], v[136:139], v[168:171], v[40:43]
	v_mfma_f32_16x16x32_bf16 v[28:31], v[112:115], v[176:179], v[28:31]
	v_mfma_f32_16x16x32_bf16 v[24:27], v[136:139], v[176:179], v[24:27]
	v_mfma_f32_16x16x32_bf16 v[12:15], v[112:115], v[220:223], v[12:15]
	v_mfma_f32_16x16x32_bf16 v[8:11], v[136:139], v[220:223], v[8:11]
	v_mfma_f32_16x16x32_bf16 v[60:63], v[124:127], v[164:167], v[60:63]
	v_mfma_f32_16x16x32_bf16 v[56:59], v[140:143], v[164:167], v[56:59]
	v_mfma_f32_16x16x32_bf16 v[44:47], v[124:127], v[172:175], v[44:47]
	v_mfma_f32_16x16x32_bf16 v[40:43], v[140:143], v[172:175], v[40:43]
	v_mfma_f32_16x16x32_bf16 v[28:31], v[124:127], v[180:183], v[28:31]
	v_mfma_f32_16x16x32_bf16 v[24:27], v[140:143], v[180:183], v[24:27]
	v_mfma_f32_16x16x32_bf16 v[12:15], v[124:127], v[224:227], v[12:15]
	v_mfma_f32_16x16x32_bf16 v[8:11], v[140:143], v[224:227], v[8:11]
	v_mfma_f32_16x16x32_bf16 v[52:55], v[144:147], v[160:163], v[52:55]
	v_mfma_f32_16x16x32_bf16 v[48:51], v[152:155], v[160:163], v[48:51]
	v_mfma_f32_16x16x32_bf16 v[36:39], v[144:147], v[168:171], v[36:39]
	v_mfma_f32_16x16x32_bf16 v[32:35], v[152:155], v[168:171], v[32:35]
	v_mfma_f32_16x16x32_bf16 v[20:23], v[144:147], v[176:179], v[20:23]
	v_mfma_f32_16x16x32_bf16 v[16:19], v[152:155], v[176:179], v[16:19]
	v_mfma_f32_16x16x32_bf16 v[4:7], v[144:147], v[220:223], v[4:7]
	v_mfma_f32_16x16x32_bf16 v[0:3], v[152:155], v[220:223], v[0:3]
	v_mfma_f32_16x16x32_bf16 v[52:55], v[148:151], v[164:167], v[52:55]
	v_mfma_f32_16x16x32_bf16 v[48:51], v[156:159], v[164:167], v[48:51]
	v_mfma_f32_16x16x32_bf16 v[36:39], v[148:151], v[172:175], v[36:39]
	v_mfma_f32_16x16x32_bf16 v[32:35], v[156:159], v[172:175], v[32:35]
	v_mfma_f32_16x16x32_bf16 v[20:23], v[148:151], v[180:183], v[20:23]
	v_mfma_f32_16x16x32_bf16 v[16:19], v[156:159], v[180:183], v[16:19]
	v_mfma_f32_16x16x32_bf16 v[4:7], v[148:151], v[224:227], v[4:7]
	v_mfma_f32_16x16x32_bf16 v[0:3], v[156:159], v[224:227], v[0:3]
	s_barrier
	ds_read_b128 v[112:115], v213
	ds_read_b128 v[124:127], v213 offset:1024
	ds_read_b128 v[136:139], v213 offset:2048
	ds_read_b128 v[140:143], v213 offset:3072
	ds_read_b128 v[144:147], v214
	ds_read_b128 v[148:151], v214 offset:1024
	ds_read_b128 v[152:155], v214 offset:2048
	ds_read_b128 v[156:159], v214 offset:3072
	s_mov_b32 m0, s18
	v_lshl_add_u64 v[228:229], v[216:217], 0, s[34:35]
	ds_read_b128 v[160:163], v212 offset:32768
	ds_read_b128 v[164:167], v212 offset:33792
	ds_read_b128 v[168:171], v212 offset:34816
	ds_read_b128 v[172:175], v212 offset:35840
	ds_read_b128 v[176:179], v212 offset:36864
	ds_read_b128 v[180:183], v212 offset:37888
	ds_read_b128 v[220:223], v212 offset:38912
	ds_read_b128 v[224:227], v212 offset:39936
	global_load_lds_dwordx4 v[228:229], off
	v_lshl_add_u64 v[228:229], v[216:217], 0, s[36:37]
	s_mov_b32 m0, s19
	s_nop 0
	global_load_lds_dwordx4 v[228:229], off
	s_waitcnt vmcnt(8)
	s_waitcnt lgkmcnt(0)
	s_barrier
	s_waitcnt lgkmcnt(0)
	v_mfma_f32_16x16x32_bf16 v[132:135], v[112:115], v[160:163], v[132:135]
	v_mfma_f32_16x16x32_bf16 v[128:131], v[136:139], v[160:163], v[128:131]
	v_mfma_f32_16x16x32_bf16 v[108:111], v[112:115], v[168:171], v[108:111]
	v_mfma_f32_16x16x32_bf16 v[104:107], v[136:139], v[168:171], v[104:107]
	v_mfma_f32_16x16x32_bf16 v[92:95], v[112:115], v[176:179], v[92:95]
	v_mfma_f32_16x16x32_bf16 v[88:91], v[136:139], v[176:179], v[88:91]
	v_mfma_f32_16x16x32_bf16 v[76:79], v[112:115], v[220:223], v[76:79]
	v_mfma_f32_16x16x32_bf16 v[72:75], v[136:139], v[220:223], v[72:75]
	v_mfma_f32_16x16x32_bf16 v[132:135], v[124:127], v[164:167], v[132:135]
	v_mfma_f32_16x16x32_bf16 v[128:131], v[140:143], v[164:167], v[128:131]
	v_mfma_f32_16x16x32_bf16 v[108:111], v[124:127], v[172:175], v[108:111]
	v_mfma_f32_16x16x32_bf16 v[104:107], v[140:143], v[172:175], v[104:107]
	v_mfma_f32_16x16x32_bf16 v[92:95], v[124:127], v[180:183], v[92:95]
	v_mfma_f32_16x16x32_bf16 v[88:91], v[140:143], v[180:183], v[88:91]
	v_mfma_f32_16x16x32_bf16 v[76:79], v[124:127], v[224:227], v[76:79]
	v_mfma_f32_16x16x32_bf16 v[72:75], v[140:143], v[224:227], v[72:75]
	v_mfma_f32_16x16x32_bf16 v[120:123], v[144:147], v[160:163], v[120:123]
	v_mfma_f32_16x16x32_bf16 v[116:119], v[152:155], v[160:163], v[116:119]
	v_mfma_f32_16x16x32_bf16 v[100:103], v[144:147], v[168:171], v[100:103]
	v_mfma_f32_16x16x32_bf16 v[96:99], v[152:155], v[168:171], v[96:99]
	v_mfma_f32_16x16x32_bf16 v[84:87], v[144:147], v[176:179], v[84:87]
	v_mfma_f32_16x16x32_bf16 v[80:83], v[152:155], v[176:179], v[80:83]
	v_mfma_f32_16x16x32_bf16 v[68:71], v[144:147], v[220:223], v[68:71]
	v_mfma_f32_16x16x32_bf16 v[64:67], v[152:155], v[220:223], v[64:67]
	v_mfma_f32_16x16x32_bf16 v[120:123], v[148:151], v[164:167], v[120:123]
	v_mfma_f32_16x16x32_bf16 v[116:119], v[156:159], v[164:167], v[116:119]
	v_mfma_f32_16x16x32_bf16 v[100:103], v[148:151], v[172:175], v[100:103]
	v_mfma_f32_16x16x32_bf16 v[96:99], v[156:159], v[172:175], v[96:99]
	v_mfma_f32_16x16x32_bf16 v[84:87], v[148:151], v[180:183], v[84:87]
	v_mfma_f32_16x16x32_bf16 v[80:83], v[156:159], v[180:183], v[80:83]
	v_mfma_f32_16x16x32_bf16 v[68:71], v[148:151], v[224:227], v[68:71]
	v_mfma_f32_16x16x32_bf16 v[64:67], v[156:159], v[224:227], v[64:67]
	s_barrier
; #define PG8_STAGE(bufoff, gbase, voff) do { _Pragma("unroll") for (int _i = 0; _i < 2; ++_i) \
;         __builtin_amdgcn_global_load_lds((const unsigned*)((const char*)(gbase) + (voff)[_i]), (PG8_LAS unsigned*)(lds + (bufoff) + ldsw + _i * 8192), 16, 0, 0); } while (0)
; #define PG8_LDA(dst, b, h) do { _Pragma("unroll") for (int m = 0; m < 4; ++m) _Pragma("unroll") for (int k = 0; k < 2; ++k) dst[m][k] = *(const PG8_LAS bf16x8*)(lds + PG8_SA(b, h) + aoff + m * 2048 + k * 1024); } while (0)
; #define PG8_MMA(ai, bj, At, Bt) do { __builtin_amdgcn_s_setprio(1); _Pragma("unroll") for (int m = 0; m < 4; ++m) _Pragma("unroll") for (int n = 0; n < 2; ++n) _Pragma("unroll") for (int k = 0; k < 2; ++k) \
;         acc[ai][bj][m][n] = __builtin_amdgcn_mfma_f32_16x16x32_bf16(Bt[n][k], At[m][k], acc[ai][bj][m][n], 0, 0, 0); __builtin_amdgcn_s_setprio(0); } while (0)
; #define PG8_WAIT_V(n) asm volatile("s_waitcnt vmcnt(" #n ")" ::: "memory")
; #define PG8_WAIT_L(n) asm volatile("s_waitcnt lgkmcnt(" #n ")" ::: "memory")
; #define PG8_BAR __builtin_amdgcn_s_barrier()
; #define PG8_SCHED __builtin_amdgcn_sched_barrier(0)
; template <class Epi, class Sched, bool ALIGN_EPI = false, bool SP2 = false>
; __device__ __forceinline__ void gemm_phase(PG8_LAS unsigned char* lds, const Gemm g, const Sched& S, const Epi& E) {
;     ...
;             PG8_LDA(At, 1, 1); PG8_STAGE(PG8_SB(1, 0), b3, voffB); PG8_STAGE(PG8_SB(1, 1), b3 + hstepB, voffB); PG8_STAGE(PG8_SA(1, 0), a3, voffA);
;             PG8_WAIT_V(8); PG8_WAIT_L(0); PG8_BAR; PG8_MMA(1, 0, At, B0); PG8_MMA(1, 1, At, B1); PG8_BAR; PG8_SCHED;
	s_add_i32 s8, s91, s14
	v_lshl_add_u64 v[228:229], v[208:209], 0, s[38:39]
	s_mov_b32 m0, s8
	ds_read_b128 v[160:163], v212 offset:49152
	ds_read_b128 v[164:167], v212 offset:50176
	ds_read_b128 v[168:171], v212 offset:51200
	ds_read_b128 v[172:175], v212 offset:52224
	ds_read_b128 v[176:179], v212 offset:53248
	ds_read_b128 v[180:183], v212 offset:54272
	ds_read_b128 v[220:223], v212 offset:55296
	ds_read_b128 v[224:227], v212 offset:56320
	global_load_lds_dwordx4 v[228:229], off
	v_lshl_add_u64 v[228:229], v[208:209], 0, s[40:41]
	s_add_i32 m0, s8, 0x2000
	s_add_i32 s8, s92, s14
	global_load_lds_dwordx4 v[228:229], off
	v_lshl_add_u64 v[228:229], v[208:209], 0, s[52:53]
	s_mov_b32 m0, s8
	v_lshl_add_u64 v[208:209], v[208:209], 0, s[54:55]
	global_load_lds_dwordx4 v[228:229], off
	s_add_i32 m0, s8, 0x2000
	s_nop 0
	global_load_lds_dwordx4 v[208:209], off
	v_lshl_add_u64 v[208:209], v[216:217], 0, s[38:39]
	s_mov_b32 m0, s78
	s_nop 0
	global_load_lds_dwordx4 v[208:209], off
	v_lshl_add_u64 v[208:209], v[216:217], 0, s[40:41]
	s_mov_b32 m0, s79
	s_nop 0
	global_load_lds_dwordx4 v[208:209], off
	s_waitcnt vmcnt(8)
	s_waitcnt lgkmcnt(0)
	s_barrier
	s_waitcnt lgkmcnt(0)
	v_mfma_f32_16x16x32_bf16 v[60:63], v[112:115], v[160:163], v[60:63]
	v_mfma_f32_16x16x32_bf16 v[56:59], v[136:139], v[160:163], v[56:59]
	v_mfma_f32_16x16x32_bf16 v[44:47], v[112:115], v[168:171], v[44:47]
	v_mfma_f32_16x16x32_bf16 v[40:43], v[136:139], v[168:171], v[40:43]
	v_mfma_f32_16x16x32_bf16 v[28:31], v[112:115], v[176:179], v[28:31]
	v_mfma_f32_16x16x32_bf16 v[24:27], v[136:139], v[176:179], v[24:27]
	v_mfma_f32_16x16x32_bf16 v[12:15], v[112:115], v[220:223], v[12:15]
	v_mfma_f32_16x16x32_bf16 v[8:11], v[136:139], v[220:223], v[8:11]
	v_mfma_f32_16x16x32_bf16 v[60:63], v[124:127], v[164:167], v[60:63]
	v_mfma_f32_16x16x32_bf16 v[56:59], v[140:143], v[164:167], v[56:59]
	v_mfma_f32_16x16x32_bf16 v[44:47], v[124:127], v[172:175], v[44:47]
	v_mfma_f32_16x16x32_bf16 v[40:43], v[140:143], v[172:175], v[40:43]
	v_mfma_f32_16x16x32_bf16 v[28:31], v[124:127], v[180:183], v[28:31]
	v_mfma_f32_16x16x32_bf16 v[24:27], v[140:143], v[180:183], v[24:27]
	v_mfma_f32_16x16x32_bf16 v[12:15], v[124:127], v[224:227], v[12:15]
	v_mfma_f32_16x16x32_bf16 v[8:11], v[140:143], v[224:227], v[8:11]
	v_mfma_f32_16x16x32_bf16 v[52:55], v[144:147], v[160:163], v[52:55]
	v_mfma_f32_16x16x32_bf16 v[48:51], v[152:155], v[160:163], v[48:51]
	v_mfma_f32_16x16x32_bf16 v[36:39], v[144:147], v[168:171], v[36:39]
	v_mfma_f32_16x16x32_bf16 v[32:35], v[152:155], v[168:171], v[32:35]
	v_mfma_f32_16x16x32_bf16 v[20:23], v[144:147], v[176:179], v[20:23]
	v_mfma_f32_16x16x32_bf16 v[16:19], v[152:155], v[176:179], v[16:19]
	v_mfma_f32_16x16x32_bf16 v[4:7], v[144:147], v[220:223], v[4:7]
	v_mfma_f32_16x16x32_bf16 v[0:3], v[152:155], v[220:223], v[0:3]
	v_mfma_f32_16x16x32_bf16 v[52:55], v[148:151], v[164:167], v[52:55]
	v_mfma_f32_16x16x32_bf16 v[48:51], v[156:159], v[164:167], v[48:51]
	v_mfma_f32_16x16x32_bf16 v[36:39], v[148:151], v[172:175], v[36:39]
	v_mfma_f32_16x16x32_bf16 v[32:35], v[156:159], v[172:175], v[32:35]
	v_mfma_f32_16x16x32_bf16 v[20:23], v[148:151], v[180:183], v[20:23]
	v_mfma_f32_16x16x32_bf16 v[16:19], v[156:159], v[180:183], v[16:19]
	v_mfma_f32_16x16x32_bf16 v[4:7], v[148:151], v[224:227], v[4:7]
	v_mfma_f32_16x16x32_bf16 v[0:3], v[156:159], v[224:227], v[0:3]
	s_barrier
	s_add_i32 s73, s73, 2
	s_add_u32 s68, s68, 0x10000
	s_addc_u32 s69, s69, 0
	s_add_u32 s70, s70, 0x10000
	s_addc_u32 s71, s71, 0
	s_cmp_gt_u32 s73, 41
	s_cbranch_scc0 .LBB0_226

; #define PG8_STAGE(bufoff, gbase, voff) do { _Pragma("unroll") for (int _i = 0; _i < 2; ++_i) \
;         __builtin_amdgcn_global_load_lds((const unsigned*)((const char*)(gbase) + (voff)[_i]), (PG8_LAS unsigned*)(lds + (bufoff) + ldsw + _i * 8192), 16, 0, 0); } while (0)
; #define PG8_LDA(dst, b, h) do { _Pragma("unroll") for (int m = 0; m < 4; ++m) _Pragma("unroll") for (int k = 0; k < 2; ++k) dst[m][k] = *(const PG8_LAS bf16x8*)(lds + PG8_SA(b, h) + aoff + m * 2048 + k * 1024); } while (0)
; #define PG8_LDB(dst, b, h) do { _Pragma("unroll") for (int n = 0; n < 2; ++n) _Pragma("unroll") for (int k = 0; k < 2; ++k) dst[n][k] = *(const PG8_LAS bf16x8*)(lds + PG8_SB(b, h) + boff + n * 2048 + k * 1024); } while (0)
; #define PG8_MMA(ai, bj, At, Bt) do { __builtin_amdgcn_s_setprio(1); _Pragma("unroll") for (int m = 0; m < 4; ++m) _Pragma("unroll") for (int n = 0; n < 2; ++n) _Pragma("unroll") for (int k = 0; k < 2; ++k) \
;         acc[ai][bj][m][n] = __builtin_amdgcn_mfma_f32_16x16x32_bf16(Bt[n][k], At[m][k], acc[ai][bj][m][n], 0, 0, 0); __builtin_amdgcn_s_setprio(0); } while (0)
; #define PG8_WAIT_V(n) asm volatile("s_waitcnt vmcnt(" #n ")" ::: "memory")
; #define PG8_WAIT_L(n) asm volatile("s_waitcnt lgkmcnt(" #n ")" ::: "memory")
; #define PG8_BAR __builtin_amdgcn_s_barrier()
; #define PG8_SCHED __builtin_amdgcn_sched_barrier(0)
;     __device__ __forceinline__ char* hb_at(const Unit& u, int ai, int m, int bj, int wr, int wc, int fr, int fq) const {
;         return (char*)hb + ((size_t)((u.pm * 16 + u.pn * 4 + bj * 2 + (wc >> 1)) * 2 + ai) * HTB) + lds_byte(wr * 64 + m * 16 + fr, (wc & 1) * 32 + 8 * fq); }
; template <class Epi, class Sched, bool ALIGN_EPI = false, bool SP2 = false>
; __device__ __forceinline__ void gemm_phase(PG8_LAS unsigned char* lds, const Gemm g, const Sched& S, const Epi& E) {
;     ...
;             PG8_LDB(B0, 0, 0); PG8_LDB(B1, 0, 1); PG8_SCHED; PG8_LDA(At, 0, 0); PG8_STAGE(PG8_SA(1, 1), a1 + hstepA, voffA);
;             PG8_WAIT_V(8); PG8_WAIT_L(0); PG8_BAR; PG8_MMA(0, 0, At, B0); PG8_MMA(0, 1, At, B1); PG8_BAR; PG8_SCHED;
;             PG8_LDA(At, 0, 1); PG8_STAGE(PG8_SB(0, 0), b2, voffB); PG8_STAGE(PG8_SB(0, 1), b2 + hstepB, voffB); PG8_STAGE(PG8_SA(0, 0), a2, voffA);
.LBB0_751:
	ds_read_b128 v[128:131], v211
	ds_read_b128 v[132:135], v211 offset:1024
	ds_read_b128 v[136:139], v211 offset:2048
	ds_read_b128 v[140:143], v211 offset:3072
	ds_read_b128 v[144:147], v212
	ds_read_b128 v[148:151], v212 offset:1024
	ds_read_b128 v[152:155], v212 offset:2048
	ds_read_b128 v[156:159], v212 offset:3072
	s_cmp_eq_u32 s72, 12
	s_cselect_b32 s79, s59, s69
	s_cselect_b32 s78, s65, s68
	s_cselect_b32 s91, s57, s71
	s_cselect_b32 s90, s67, s70
	s_cmp_eq_u32 s72, 12
	s_cbranch_scc0 .Lhbpf_skip_5
	s_lshl_b32 s98, s64, 5
	s_lshl_b32 s99, s66, 3
	s_add_i32 s98, s98, s99
	s_mov_b32 s99, 0
	s_lshl_b64 s[98:99], s[98:99], 14
	s_add_u32 s98, s98, s22
	s_addc_u32 s99, s99, s23
	s_add_u32 s98, s98, 0x3000000
	s_addc_u32 s99, s99, 0
	v_readlane_b32 s100, v246, 6
	v_mbcnt_lo_u32_b32 v247, -1, 0
	v_mbcnt_hi_u32_b32 v247, -1, v247
	s_nop 1
	v_lshl_add_u32 v247, s100, 6, v247
	v_lshlrev_b32_e32 v247, 7, v247
	v_add_u32_e32 v249, 0x10000, v247
	s_nop 0
	global_load_dword v248, v247, s[98:99]
	global_load_dword v248, v249, s[98:99]
.Lhbpf_skip_5:
	v_lshl_add_u64 v[208:209], s[68:69], 0, v[190:191]
	v_lshl_add_u64 v[228:229], v[208:209], 0, s[52:53]
	s_add_i32 m0, s15, 0xc000
	ds_read_b128 v[160:163], v213
	ds_read_b128 v[164:167], v213 offset:1024
	ds_read_b128 v[168:171], v213 offset:2048
	ds_read_b128 v[172:175], v213 offset:3072
	ds_read_b128 v[176:179], v213 offset:4096
	ds_read_b128 v[180:183], v213 offset:5120
	ds_read_b128 v[220:223], v213 offset:6144
	ds_read_b128 v[224:227], v213 offset:7168
	global_load_lds_dwordx4 v[228:229], off
	v_lshl_add_u64 v[208:209], v[208:209], 0, s[54:55]
	s_add_i32 m0, s15, 0xe000
	s_nop 0
	global_load_lds_dwordx4 v[208:209], off
	s_waitcnt vmcnt(8)
	s_waitcnt lgkmcnt(0)
	s_barrier
	s_waitcnt lgkmcnt(0)
	v_mfma_f32_16x16x32_bf16 v[124:127], v[128:131], v[160:163], v[124:127]
	v_mfma_f32_16x16x32_bf16 v[120:123], v[136:139], v[160:163], v[120:123]
	v_mfma_f32_16x16x32_bf16 v[108:111], v[128:131], v[168:171], v[108:111]
	v_mfma_f32_16x16x32_bf16 v[104:107], v[136:139], v[168:171], v[104:107]
	v_mfma_f32_16x16x32_bf16 v[92:95], v[128:131], v[176:179], v[92:95]
	v_mfma_f32_16x16x32_bf16 v[88:91], v[136:139], v[176:179], v[88:91]
	v_mfma_f32_16x16x32_bf16 v[76:79], v[128:131], v[220:223], v[76:79]
	v_mfma_f32_16x16x32_bf16 v[72:75], v[136:139], v[220:223], v[72:75]
	v_mfma_f32_16x16x32_bf16 v[124:127], v[132:135], v[164:167], v[124:127]
	v_mfma_f32_16x16x32_bf16 v[120:123], v[140:143], v[164:167], v[120:123]
	v_mfma_f32_16x16x32_bf16 v[108:111], v[132:135], v[172:175], v[108:111]
	v_mfma_f32_16x16x32_bf16 v[104:107], v[140:143], v[172:175], v[104:107]
	v_mfma_f32_16x16x32_bf16 v[92:95], v[132:135], v[180:183], v[92:95]
	v_mfma_f32_16x16x32_bf16 v[88:91], v[140:143], v[180:183], v[88:91]
	v_mfma_f32_16x16x32_bf16 v[76:79], v[132:135], v[224:227], v[76:79]
	v_mfma_f32_16x16x32_bf16 v[72:75], v[140:143], v[224:227], v[72:75]
	v_mfma_f32_16x16x32_bf16 v[116:119], v[144:147], v[160:163], v[116:119]
	v_mfma_f32_16x16x32_bf16 v[112:115], v[152:155], v[160:163], v[112:115]
	v_mfma_f32_16x16x32_bf16 v[100:103], v[144:147], v[168:171], v[100:103]
	v_mfma_f32_16x16x32_bf16 v[96:99], v[152:155], v[168:171], v[96:99]
	v_mfma_f32_16x16x32_bf16 v[84:87], v[144:147], v[176:179], v[84:87]
	v_mfma_f32_16x16x32_bf16 v[80:83], v[152:155], v[176:179], v[80:83]
	v_mfma_f32_16x16x32_bf16 v[68:71], v[144:147], v[220:223], v[68:71]
	v_mfma_f32_16x16x32_bf16 v[64:67], v[152:155], v[220:223], v[64:67]
	v_mfma_f32_16x16x32_bf16 v[116:119], v[148:151], v[164:167], v[116:119]
	v_mfma_f32_16x16x32_bf16 v[112:115], v[156:159], v[164:167], v[112:115]
	v_mfma_f32_16x16x32_bf16 v[100:103], v[148:151], v[172:175], v[100:103]
	v_mfma_f32_16x16x32_bf16 v[96:99], v[156:159], v[172:175], v[96:99]
	v_mfma_f32_16x16x32_bf16 v[84:87], v[148:151], v[180:183], v[84:87]
	v_mfma_f32_16x16x32_bf16 v[80:83], v[156:159], v[180:183], v[80:83]
	v_mfma_f32_16x16x32_bf16 v[68:71], v[148:151], v[224:227], v[68:71]
	v_mfma_f32_16x16x32_bf16 v[64:67], v[156:159], v[224:227], v[64:67]
	s_barrier
	s_add_i32 s73, s85, s14
	v_lshl_add_u64 v[208:209], s[90:91], 0, v[190:191]
	s_mov_b32 m0, s73
	ds_read_b128 v[160:163], v213 offset:16384
	ds_read_b128 v[164:167], v213 offset:17408
	ds_read_b128 v[168:171], v213 offset:18432
	ds_read_b128 v[172:175], v213 offset:19456
	ds_read_b128 v[176:179], v213 offset:20480
	ds_read_b128 v[180:183], v213 offset:21504
	ds_read_b128 v[220:223], v213 offset:22528
	ds_read_b128 v[224:227], v213 offset:23552
	global_load_lds_dwordx4 v[208:209], off
	v_lshl_add_u64 v[228:229], v[208:209], 0, s[10:11]
	s_add_i32 m0, s73, 0x2000
	s_add_i32 s73, s86, s14
	global_load_lds_dwordx4 v[228:229], off
	v_lshl_add_u64 v[228:229], v[208:209], 0, s[34:35]
	s_mov_b32 m0, s73
	s_nop 0
	global_load_lds_dwordx4 v[228:229], off
	v_lshl_add_u64 v[228:229], v[208:209], 0, s[36:37]
	s_add_i32 m0, s73, 0x2000
	s_nop 0
	global_load_lds_dwordx4 v[228:229], off
	v_lshl_add_u64 v[228:229], s[78:79], 0, v[190:191]
	s_mov_b32 m0, s15
	v_lshl_add_u64 v[230:231], v[228:229], 0, s[10:11]
	global_load_lds_dwordx4 v[228:229], off
	s_mov_b32 m0, s17
	s_nop 0
	global_load_lds_dwordx4 v[230:231], off
	s_waitcnt vmcnt(8)
	s_waitcnt lgkmcnt(0)
	s_barrier
; #define PG8_STAGE(bufoff, gbase, voff) do { _Pragma("unroll") for (int _i = 0; _i < 2; ++_i) \
;         __builtin_amdgcn_global_load_lds((const unsigned*)((const char*)(gbase) + (voff)[_i]), (PG8_LAS unsigned*)(lds + (bufoff) + ldsw + _i * 8192), 16, 0, 0); } while (0)
; #define PG8_LDA(dst, b, h) do { _Pragma("unroll") for (int m = 0; m < 4; ++m) _Pragma("unroll") for (int k = 0; k < 2; ++k) dst[m][k] = *(const PG8_LAS bf16x8*)(lds + PG8_SA(b, h) + aoff + m * 2048 + k * 1024); } while (0)
; #define PG8_LDB(dst, b, h) do { _Pragma("unroll") for (int n = 0; n < 2; ++n) _Pragma("unroll") for (int k = 0; k < 2; ++k) dst[n][k] = *(const PG8_LAS bf16x8*)(lds + PG8_SB(b, h) + boff + n * 2048 + k * 1024); } while (0)
; #define PG8_MMA(ai, bj, At, Bt) do { __builtin_amdgcn_s_setprio(1); _Pragma("unroll") for (int m = 0; m < 4; ++m) _Pragma("unroll") for (int n = 0; n < 2; ++n) _Pragma("unroll") for (int k = 0; k < 2; ++k) \
;         acc[ai][bj][m][n] = __builtin_amdgcn_mfma_f32_16x16x32_bf16(Bt[n][k], At[m][k], acc[ai][bj][m][n], 0, 0, 0); __builtin_amdgcn_s_setprio(0); } while (0)
; #define PG8_WAIT_V(n) asm volatile("s_waitcnt vmcnt(" #n ")" ::: "memory")
; #define PG8_WAIT_L(n) asm volatile("s_waitcnt lgkmcnt(" #n ")" ::: "memory")
; #define PG8_BAR __builtin_amdgcn_s_barrier()
; #define PG8_SCHED __builtin_amdgcn_sched_barrier(0)
; template <class Epi, class Sched, bool ALIGN_EPI = false, bool SP2 = false>
; __device__ __forceinline__ void gemm_phase(PG8_LAS unsigned char* lds, const Gemm g, const Sched& S, const Epi& E) {
;     ...
;             PG8_WAIT_V(8); PG8_WAIT_L(0); PG8_BAR; PG8_MMA(1, 0, At, B0); PG8_MMA(1, 1, At, B1); PG8_BAR; PG8_SCHED;
;             PG8_LDB(B0, 1, 0); PG8_LDB(B1, 1, 1); PG8_SCHED; PG8_LDA(At, 1, 0); PG8_STAGE(PG8_SA(0, 1), a2 + hstepA, voffA);
;             PG8_WAIT_V(8); PG8_WAIT_L(0); PG8_BAR; PG8_MMA(0, 0, At, B0); PG8_MMA(0, 1, At, B1); PG8_BAR; PG8_SCHED;
	s_waitcnt lgkmcnt(0)
	v_mfma_f32_16x16x32_bf16 v[60:63], v[128:131], v[160:163], v[60:63]
	v_mfma_f32_16x16x32_bf16 v[56:59], v[136:139], v[160:163], v[56:59]
	v_mfma_f32_16x16x32_bf16 v[44:47], v[128:131], v[168:171], v[44:47]
	v_mfma_f32_16x16x32_bf16 v[40:43], v[136:139], v[168:171], v[40:43]
	v_mfma_f32_16x16x32_bf16 v[28:31], v[128:131], v[176:179], v[28:31]
	v_mfma_f32_16x16x32_bf16 v[24:27], v[136:139], v[176:179], v[24:27]
	v_mfma_f32_16x16x32_bf16 v[12:15], v[128:131], v[220:223], v[12:15]
	v_mfma_f32_16x16x32_bf16 v[8:11], v[136:139], v[220:223], v[8:11]
	v_mfma_f32_16x16x32_bf16 v[60:63], v[132:135], v[164:167], v[60:63]
	v_mfma_f32_16x16x32_bf16 v[56:59], v[140:143], v[164:167], v[56:59]
	v_mfma_f32_16x16x32_bf16 v[44:47], v[132:135], v[172:175], v[44:47]
	v_mfma_f32_16x16x32_bf16 v[40:43], v[140:143], v[172:175], v[40:43]
	v_mfma_f32_16x16x32_bf16 v[28:31], v[132:135], v[180:183], v[28:31]
	v_mfma_f32_16x16x32_bf16 v[24:27], v[140:143], v[180:183], v[24:27]
	v_mfma_f32_16x16x32_bf16 v[12:15], v[132:135], v[224:227], v[12:15]
	v_mfma_f32_16x16x32_bf16 v[8:11], v[140:143], v[224:227], v[8:11]
	v_mfma_f32_16x16x32_bf16 v[52:55], v[144:147], v[160:163], v[52:55]
	v_mfma_f32_16x16x32_bf16 v[48:51], v[152:155], v[160:163], v[48:51]
	v_mfma_f32_16x16x32_bf16 v[36:39], v[144:147], v[168:171], v[36:39]
	v_mfma_f32_16x16x32_bf16 v[32:35], v[152:155], v[168:171], v[32:35]
	v_mfma_f32_16x16x32_bf16 v[20:23], v[144:147], v[176:179], v[20:23]
	v_mfma_f32_16x16x32_bf16 v[16:19], v[152:155], v[176:179], v[16:19]
	v_mfma_f32_16x16x32_bf16 v[4:7], v[144:147], v[220:223], v[4:7]
	v_mfma_f32_16x16x32_bf16 v[0:3], v[152:155], v[220:223], v[0:3]
	v_mfma_f32_16x16x32_bf16 v[52:55], v[148:151], v[164:167], v[52:55]
	v_mfma_f32_16x16x32_bf16 v[48:51], v[156:159], v[164:167], v[48:51]
	v_mfma_f32_16x16x32_bf16 v[36:39], v[148:151], v[172:175], v[36:39]
	v_mfma_f32_16x16x32_bf16 v[32:35], v[156:159], v[172:175], v[32:35]
	v_mfma_f32_16x16x32_bf16 v[20:23], v[148:151], v[180:183], v[20:23]
	v_mfma_f32_16x16x32_bf16 v[16:19], v[156:159], v[180:183], v[16:19]
	v_mfma_f32_16x16x32_bf16 v[4:7], v[148:151], v[224:227], v[4:7]
	v_mfma_f32_16x16x32_bf16 v[0:3], v[156:159], v[224:227], v[0:3]
	s_barrier
	ds_read_b128 v[128:131], v214
	ds_read_b128 v[132:135], v214 offset:1024
	ds_read_b128 v[136:139], v214 offset:2048
	ds_read_b128 v[140:143], v214 offset:3072
	ds_read_b128 v[144:147], v215
	ds_read_b128 v[148:151], v215 offset:1024
	ds_read_b128 v[152:155], v215 offset:2048
	ds_read_b128 v[156:159], v215 offset:3072
	s_mov_b32 m0, s18
	v_lshl_add_u64 v[230:231], v[228:229], 0, s[34:35]
	ds_read_b128 v[160:163], v213 offset:32768
	ds_read_b128 v[164:167], v213 offset:33792
	ds_read_b128 v[168:171], v213 offset:34816
	ds_read_b128 v[172:175], v213 offset:35840
	ds_read_b128 v[176:179], v213 offset:36864
	ds_read_b128 v[180:183], v213 offset:37888
	ds_read_b128 v[220:223], v213 offset:38912
	ds_read_b128 v[224:227], v213 offset:39936
	global_load_lds_dwordx4 v[230:231], off
	v_lshl_add_u64 v[230:231], v[228:229], 0, s[36:37]
	s_mov_b32 m0, s19
	s_nop 0
	global_load_lds_dwordx4 v[230:231], off
	s_waitcnt vmcnt(8)
	s_waitcnt lgkmcnt(0)
	s_barrier
	s_waitcnt lgkmcnt(0)
	v_mfma_f32_16x16x32_bf16 v[124:127], v[128:131], v[160:163], v[124:127]
	v_mfma_f32_16x16x32_bf16 v[120:123], v[136:139], v[160:163], v[120:123]
	v_mfma_f32_16x16x32_bf16 v[108:111], v[128:131], v[168:171], v[108:111]
	v_mfma_f32_16x16x32_bf16 v[104:107], v[136:139], v[168:171], v[104:107]
	v_mfma_f32_16x16x32_bf16 v[92:95], v[128:131], v[176:179], v[92:95]
	v_mfma_f32_16x16x32_bf16 v[88:91], v[136:139], v[176:179], v[88:91]
	v_mfma_f32_16x16x32_bf16 v[76:79], v[128:131], v[220:223], v[76:79]
	v_mfma_f32_16x16x32_bf16 v[72:75], v[136:139], v[220:223], v[72:75]
	v_mfma_f32_16x16x32_bf16 v[124:127], v[132:135], v[164:167], v[124:127]
	v_mfma_f32_16x16x32_bf16 v[120:123], v[140:143], v[164:167], v[120:123]
	v_mfma_f32_16x16x32_bf16 v[108:111], v[132:135], v[172:175], v[108:111]
	v_mfma_f32_16x16x32_bf16 v[104:107], v[140:143], v[172:175], v[104:107]
	v_mfma_f32_16x16x32_bf16 v[92:95], v[132:135], v[180:183], v[92:95]
	v_mfma_f32_16x16x32_bf16 v[88:91], v[140:143], v[180:183], v[88:91]
	v_mfma_f32_16x16x32_bf16 v[76:79], v[132:135], v[224:227], v[76:79]
	v_mfma_f32_16x16x32_bf16 v[72:75], v[140:143], v[224:227], v[72:75]
	v_mfma_f32_16x16x32_bf16 v[116:119], v[144:147], v[160:163], v[116:119]
	v_mfma_f32_16x16x32_bf16 v[112:115], v[152:155], v[160:163], v[112:115]
	v_mfma_f32_16x16x32_bf16 v[100:103], v[144:147], v[168:171], v[100:103]
	v_mfma_f32_16x16x32_bf16 v[96:99], v[152:155], v[168:171], v[96:99]
	v_mfma_f32_16x16x32_bf16 v[84:87], v[144:147], v[176:179], v[84:87]
	v_mfma_f32_16x16x32_bf16 v[80:83], v[152:155], v[176:179], v[80:83]
	v_mfma_f32_16x16x32_bf16 v[68:71], v[144:147], v[220:223], v[68:71]
	v_mfma_f32_16x16x32_bf16 v[64:67], v[152:155], v[220:223], v[64:67]
	v_mfma_f32_16x16x32_bf16 v[116:119], v[148:151], v[164:167], v[116:119]
	v_mfma_f32_16x16x32_bf16 v[112:115], v[156:159], v[164:167], v[112:115]
	v_mfma_f32_16x16x32_bf16 v[100:103], v[148:151], v[172:175], v[100:103]
	v_mfma_f32_16x16x32_bf16 v[96:99], v[156:159], v[172:175], v[96:99]
	v_mfma_f32_16x16x32_bf16 v[84:87], v[148:151], v[180:183], v[84:87]
	v_mfma_f32_16x16x32_bf16 v[80:83], v[156:159], v[180:183], v[80:83]
	v_mfma_f32_16x16x32_bf16 v[68:71], v[148:151], v[224:227], v[68:71]
	v_mfma_f32_16x16x32_bf16 v[64:67], v[156:159], v[224:227], v[64:67]
	s_barrier
; #define PG8_STAGE(bufoff, gbase, voff) do { _Pragma("unroll") for (int _i = 0; _i < 2; ++_i) \
;         __builtin_amdgcn_global_load_lds((const unsigned*)((const char*)(gbase) + (voff)[_i]), (PG8_LAS unsigned*)(lds + (bufoff) + ldsw + _i * 8192), 16, 0, 0); } while (0)
; #define PG8_LDA(dst, b, h) do { _Pragma("unroll") for (int m = 0; m < 4; ++m) _Pragma("unroll") for (int k = 0; k < 2; ++k) dst[m][k] = *(const PG8_LAS bf16x8*)(lds + PG8_SA(b, h) + aoff + m * 2048 + k * 1024); } while (0)
; #define PG8_MMA(ai, bj, At, Bt) do { __builtin_amdgcn_s_setprio(1); _Pragma("unroll") for (int m = 0; m < 4; ++m) _Pragma("unroll") for (int n = 0; n < 2; ++n) _Pragma("unroll") for (int k = 0; k < 2; ++k) \
;         acc[ai][bj][m][n] = __builtin_amdgcn_mfma_f32_16x16x32_bf16(Bt[n][k], At[m][k], acc[ai][bj][m][n], 0, 0, 0); __builtin_amdgcn_s_setprio(0); } while (0)
; #define PG8_WAIT_V(n) asm volatile("s_waitcnt vmcnt(" #n ")" ::: "memory")
; #define PG8_WAIT_L(n) asm volatile("s_waitcnt lgkmcnt(" #n ")" ::: "memory")
; #define PG8_BAR __builtin_amdgcn_s_barrier()
; #define PG8_SCHED __builtin_amdgcn_sched_barrier(0)
; template <class Epi, class Sched, bool ALIGN_EPI = false, bool SP2 = false>
; __device__ __forceinline__ void gemm_phase(PG8_LAS unsigned char* lds, const Gemm g, const Sched& S, const Epi& E) {
;     ...
;             PG8_LDA(At, 1, 1); PG8_STAGE(PG8_SB(1, 0), b3, voffB); PG8_STAGE(PG8_SB(1, 1), b3 + hstepB, voffB); PG8_STAGE(PG8_SA(1, 0), a3, voffA);
;             PG8_WAIT_V(8); PG8_WAIT_L(0); PG8_BAR; PG8_MMA(1, 0, At, B0); PG8_MMA(1, 1, At, B1); PG8_BAR; PG8_SCHED;
	s_add_i32 s73, s87, s14
	v_lshl_add_u64 v[230:231], v[208:209], 0, s[38:39]
	s_mov_b32 m0, s73
	ds_read_b128 v[160:163], v213 offset:49152
	ds_read_b128 v[164:167], v213 offset:50176
	ds_read_b128 v[168:171], v213 offset:51200
	ds_read_b128 v[172:175], v213 offset:52224
	ds_read_b128 v[176:179], v213 offset:53248
	ds_read_b128 v[180:183], v213 offset:54272
	ds_read_b128 v[220:223], v213 offset:55296
	ds_read_b128 v[224:227], v213 offset:56320
	global_load_lds_dwordx4 v[230:231], off
	v_lshl_add_u64 v[230:231], v[208:209], 0, s[40:41]
	s_add_i32 m0, s73, 0x2000
	s_add_i32 s73, s88, s14
	global_load_lds_dwordx4 v[230:231], off
	v_lshl_add_u64 v[230:231], v[208:209], 0, s[42:43]
	s_mov_b32 m0, s73
	v_lshl_add_u64 v[208:209], v[208:209], 0, s[44:45]
	global_load_lds_dwordx4 v[230:231], off
	s_add_i32 m0, s73, 0x2000
	s_nop 0
	global_load_lds_dwordx4 v[208:209], off
	v_lshl_add_u64 v[208:209], v[228:229], 0, s[38:39]
	s_mov_b32 m0, s74
	s_nop 0
	global_load_lds_dwordx4 v[208:209], off
	v_lshl_add_u64 v[208:209], v[228:229], 0, s[40:41]
	s_mov_b32 m0, s75
	s_nop 0
	global_load_lds_dwordx4 v[208:209], off
	s_waitcnt vmcnt(8)
	s_waitcnt lgkmcnt(0)
	s_barrier
	s_waitcnt lgkmcnt(0)
	v_mfma_f32_16x16x32_bf16 v[60:63], v[128:131], v[160:163], v[60:63]
	v_mfma_f32_16x16x32_bf16 v[56:59], v[136:139], v[160:163], v[56:59]
	v_mfma_f32_16x16x32_bf16 v[44:47], v[128:131], v[168:171], v[44:47]
	v_mfma_f32_16x16x32_bf16 v[40:43], v[136:139], v[168:171], v[40:43]
	v_mfma_f32_16x16x32_bf16 v[28:31], v[128:131], v[176:179], v[28:31]
	v_mfma_f32_16x16x32_bf16 v[24:27], v[136:139], v[176:179], v[24:27]
	v_mfma_f32_16x16x32_bf16 v[12:15], v[128:131], v[220:223], v[12:15]
	v_mfma_f32_16x16x32_bf16 v[8:11], v[136:139], v[220:223], v[8:11]
	v_mfma_f32_16x16x32_bf16 v[60:63], v[132:135], v[164:167], v[60:63]
	v_mfma_f32_16x16x32_bf16 v[56:59], v[140:143], v[164:167], v[56:59]
	v_mfma_f32_16x16x32_bf16 v[44:47], v[132:135], v[172:175], v[44:47]
	v_mfma_f32_16x16x32_bf16 v[40:43], v[140:143], v[172:175], v[40:43]
	v_mfma_f32_16x16x32_bf16 v[28:31], v[132:135], v[180:183], v[28:31]
	v_mfma_f32_16x16x32_bf16 v[24:27], v[140:143], v[180:183], v[24:27]
	v_mfma_f32_16x16x32_bf16 v[12:15], v[132:135], v[224:227], v[12:15]
	v_mfma_f32_16x16x32_bf16 v[8:11], v[140:143], v[224:227], v[8:11]
	v_mfma_f32_16x16x32_bf16 v[52:55], v[144:147], v[160:163], v[52:55]
	v_mfma_f32_16x16x32_bf16 v[48:51], v[152:155], v[160:163], v[48:51]
	v_mfma_f32_16x16x32_bf16 v[36:39], v[144:147], v[168:171], v[36:39]
	v_mfma_f32_16x16x32_bf16 v[32:35], v[152:155], v[168:171], v[32:35]
	v_mfma_f32_16x16x32_bf16 v[20:23], v[144:147], v[176:179], v[20:23]
	v_mfma_f32_16x16x32_bf16 v[16:19], v[152:155], v[176:179], v[16:19]
	v_mfma_f32_16x16x32_bf16 v[4:7], v[144:147], v[220:223], v[4:7]
	v_mfma_f32_16x16x32_bf16 v[0:3], v[152:155], v[220:223], v[0:3]
	v_mfma_f32_16x16x32_bf16 v[52:55], v[148:151], v[164:167], v[52:55]
	v_mfma_f32_16x16x32_bf16 v[48:51], v[156:159], v[164:167], v[48:51]
	v_mfma_f32_16x16x32_bf16 v[36:39], v[148:151], v[172:175], v[36:39]
	v_mfma_f32_16x16x32_bf16 v[32:35], v[156:159], v[172:175], v[32:35]
	v_mfma_f32_16x16x32_bf16 v[20:23], v[148:151], v[180:183], v[20:23]
	v_mfma_f32_16x16x32_bf16 v[16:19], v[156:159], v[180:183], v[16:19]
	v_mfma_f32_16x16x32_bf16 v[4:7], v[148:151], v[224:227], v[4:7]
	v_mfma_f32_16x16x32_bf16 v[0:3], v[156:159], v[224:227], v[0:3]
	s_barrier
	s_add_i32 s72, s72, 2
	s_add_u32 s68, s68, 0x10000
	s_addc_u32 s69, s69, 0
	s_add_u32 s70, s70, 0x10000
	s_addc_u32 s71, s71, 0
	s_cmp_gt_u32 s72, 13
	s_cbranch_scc0 .LBB0_751

; #define PG8_STAGE(bufoff, gbase, voff) do { _Pragma("unroll") for (int _i = 0; _i < 2; ++_i) \
;         __builtin_amdgcn_global_load_lds((const unsigned*)((const char*)(gbase) + (voff)[_i]), (PG8_LAS unsigned*)(lds + (bufoff) + ldsw + _i * 8192), 16, 0, 0); } while (0)
; #define PG8_LDA(dst, b, h) do { _Pragma("unroll") for (int m = 0; m < 4; ++m) _Pragma("unroll") for (int k = 0; k < 2; ++k) dst[m][k] = *(const PG8_LAS bf16x8*)(lds + PG8_SA(b, h) + aoff + m * 2048 + k * 1024); } while (0)
; #define PG8_LDB(dst, b, h) do { _Pragma("unroll") for (int n = 0; n < 2; ++n) _Pragma("unroll") for (int k = 0; k < 2; ++k) dst[n][k] = *(const PG8_LAS bf16x8*)(lds + PG8_SB(b, h) + boff + n * 2048 + k * 1024); } while (0)
; #define PG8_MMA(ai, bj, At, Bt) do { __builtin_amdgcn_s_setprio(1); _Pragma("unroll") for (int m = 0; m < 4; ++m) _Pragma("unroll") for (int n = 0; n < 2; ++n) _Pragma("unroll") for (int k = 0; k < 2; ++k) \
;         acc[ai][bj][m][n] = __builtin_amdgcn_mfma_f32_16x16x32_bf16(Bt[n][k], At[m][k], acc[ai][bj][m][n], 0, 0, 0); __builtin_amdgcn_s_setprio(0); } while (0)
; #define PG8_WAIT_V(n) asm volatile("s_waitcnt vmcnt(" #n ")" ::: "memory")
; #define PG8_WAIT_L(n) asm volatile("s_waitcnt lgkmcnt(" #n ")" ::: "memory")
; #define PG8_BAR __builtin_amdgcn_s_barrier()
; #define PG8_SCHED __builtin_amdgcn_sched_barrier(0)
;     __device__ __forceinline__ void operator()(f32x4 (&acc)[2][2][4][2], const Unit& u, int wr, int wc, int fr, int fq) const {
;     ...
;                 for (int bj = 0; bj < 2; ++bj) pre[ai][m][bj] = *(const u32x4*)((const char*)base + ((size_t)((u.pm * 16 + u.pn * 4 + bj * 2 + (wc >> 1)) * 2 + ai) * HTB) + lds_byte(wr * 64 + m * 16 + fr, (wc & 1) * 32 + 8 * fq));
; template <class Epi, class Sched, bool ALIGN_EPI = false, bool SP2 = false>
; __device__ __forceinline__ void gemm_phase(PG8_LAS unsigned char* lds, const Gemm g, const Sched& S, const Epi& E) {
;     ...
;             PG8_LDB(B0, 0, 0); PG8_LDB(B1, 0, 1); PG8_SCHED; PG8_LDA(At, 0, 0); PG8_STAGE(PG8_SA(1, 1), a1 + hstepA, voffA);
;             PG8_WAIT_V(8); PG8_WAIT_L(0); PG8_BAR; PG8_MMA(0, 0, At, B0); PG8_MMA(0, 1, At, B1); PG8_BAR; PG8_SCHED;
;             PG8_LDA(At, 0, 1); PG8_STAGE(PG8_SB(0, 0), b2, voffB); PG8_STAGE(PG8_SB(0, 1), b2 + hstepB, voffB); PG8_STAGE(PG8_SA(0, 0), a2, voffA);
.LBB0_1004:
	ds_read_b128 v[128:131], v220
	ds_read_b128 v[132:135], v220 offset:1024
	ds_read_b128 v[136:139], v220 offset:2048
	ds_read_b128 v[140:143], v220 offset:3072
	ds_read_b128 v[144:147], v221
	ds_read_b128 v[148:151], v221 offset:1024
	ds_read_b128 v[152:155], v221 offset:2048
	ds_read_b128 v[156:159], v221 offset:3072
	s_cmp_eq_u32 s73, 40
	s_cselect_b32 s75, s1, s71
	s_cselect_b32 s74, s0, s70
	s_cselect_b32 s77, s67, s72
	s_cselect_b32 s76, s66, s69
	s_cmp_eq_u32 s73, 40
	s_cbranch_scc0 .Lhbpf_skip_8
	s_lshl_b32 s98, s93, 5
	s_lshl_b32 s99, s68, 3
	s_add_i32 s98, s98, s99
	s_mov_b32 s99, 0
	s_lshl_b64 s[98:99], s[98:99], 14
	s_add_u32 s98, s98, s22
	s_addc_u32 s99, s99, s23
	s_add_u32 s98, s98, 0x3000000
	s_addc_u32 s99, s99, 0
	v_readlane_b32 s100, v246, 6
	v_mbcnt_lo_u32_b32 v247, -1, 0
	v_mbcnt_hi_u32_b32 v247, -1, v247
	s_nop 1
	v_lshl_add_u32 v247, s100, 6, v247
	v_lshlrev_b32_e32 v247, 7, v247
	v_add_u32_e32 v249, 0x10000, v247
	s_nop 0
	global_load_dword v248, v247, s[98:99]
	global_load_dword v248, v249, s[98:99]
.Lhbpf_skip_8:
	v_lshl_add_u64 v[238:239], s[70:71], 0, v[190:191]
	v_lshl_add_u64 v[240:241], v[238:239], 0, s[62:63]
	s_add_i32 m0, s15, 0xc000
	ds_read_b128 v[160:163], v222
	ds_read_b128 v[164:167], v222 offset:1024
	ds_read_b128 v[168:171], v222 offset:2048
	ds_read_b128 v[172:175], v222 offset:3072
	ds_read_b128 v[176:179], v222 offset:4096
	ds_read_b128 v[180:183], v222 offset:5120
	ds_read_b128 v[230:233], v222 offset:6144
	ds_read_b128 v[234:237], v222 offset:7168
	global_load_lds_dwordx4 v[240:241], off
	v_lshl_add_u64 v[238:239], v[238:239], 0, s[64:65]
	s_add_i32 m0, s15, 0xe000
	s_nop 0
	global_load_lds_dwordx4 v[238:239], off
	s_waitcnt vmcnt(8)
	s_waitcnt lgkmcnt(0)
	s_barrier
	s_waitcnt lgkmcnt(0)
	v_mfma_f32_16x16x32_bf16 v[124:127], v[128:131], v[160:163], v[124:127]
	v_mfma_f32_16x16x32_bf16 v[120:123], v[136:139], v[160:163], v[120:123]
	v_mfma_f32_16x16x32_bf16 v[108:111], v[128:131], v[168:171], v[108:111]
	v_mfma_f32_16x16x32_bf16 v[104:107], v[136:139], v[168:171], v[104:107]
	v_mfma_f32_16x16x32_bf16 v[92:95], v[128:131], v[176:179], v[92:95]
	v_mfma_f32_16x16x32_bf16 v[88:91], v[136:139], v[176:179], v[88:91]
	v_mfma_f32_16x16x32_bf16 v[76:79], v[128:131], v[230:233], v[76:79]
	v_mfma_f32_16x16x32_bf16 v[72:75], v[136:139], v[230:233], v[72:75]
	v_mfma_f32_16x16x32_bf16 v[124:127], v[132:135], v[164:167], v[124:127]
	v_mfma_f32_16x16x32_bf16 v[120:123], v[140:143], v[164:167], v[120:123]
	v_mfma_f32_16x16x32_bf16 v[108:111], v[132:135], v[172:175], v[108:111]
	v_mfma_f32_16x16x32_bf16 v[104:107], v[140:143], v[172:175], v[104:107]
	v_mfma_f32_16x16x32_bf16 v[92:95], v[132:135], v[180:183], v[92:95]
	v_mfma_f32_16x16x32_bf16 v[88:91], v[140:143], v[180:183], v[88:91]
	v_mfma_f32_16x16x32_bf16 v[76:79], v[132:135], v[234:237], v[76:79]
	v_mfma_f32_16x16x32_bf16 v[72:75], v[140:143], v[234:237], v[72:75]
	v_mfma_f32_16x16x32_bf16 v[116:119], v[144:147], v[160:163], v[116:119]
	v_mfma_f32_16x16x32_bf16 v[112:115], v[152:155], v[160:163], v[112:115]
	v_mfma_f32_16x16x32_bf16 v[100:103], v[144:147], v[168:171], v[100:103]
	v_mfma_f32_16x16x32_bf16 v[96:99], v[152:155], v[168:171], v[96:99]
	v_mfma_f32_16x16x32_bf16 v[84:87], v[144:147], v[176:179], v[84:87]
	v_mfma_f32_16x16x32_bf16 v[80:83], v[152:155], v[176:179], v[80:83]
	v_mfma_f32_16x16x32_bf16 v[68:71], v[144:147], v[230:233], v[68:71]
	v_mfma_f32_16x16x32_bf16 v[64:67], v[152:155], v[230:233], v[64:67]
	v_mfma_f32_16x16x32_bf16 v[116:119], v[148:151], v[164:167], v[116:119]
	v_mfma_f32_16x16x32_bf16 v[112:115], v[156:159], v[164:167], v[112:115]
	v_mfma_f32_16x16x32_bf16 v[100:103], v[148:151], v[172:175], v[100:103]
	v_mfma_f32_16x16x32_bf16 v[96:99], v[156:159], v[172:175], v[96:99]
	v_mfma_f32_16x16x32_bf16 v[84:87], v[148:151], v[180:183], v[84:87]
	v_mfma_f32_16x16x32_bf16 v[80:83], v[156:159], v[180:183], v[80:83]
	v_mfma_f32_16x16x32_bf16 v[68:71], v[148:151], v[234:237], v[68:71]
	v_mfma_f32_16x16x32_bf16 v[64:67], v[156:159], v[234:237], v[64:67]
	s_barrier
	s_add_i32 s33, s86, s14
	v_lshl_add_u64 v[238:239], s[76:77], 0, v[190:191]
	s_mov_b32 m0, s33
	ds_read_b128 v[160:163], v222 offset:16384
	ds_read_b128 v[164:167], v222 offset:17408
	ds_read_b128 v[168:171], v222 offset:18432
	ds_read_b128 v[172:175], v222 offset:19456
	ds_read_b128 v[176:179], v222 offset:20480
	ds_read_b128 v[180:183], v222 offset:21504
	ds_read_b128 v[230:233], v222 offset:22528
	ds_read_b128 v[234:237], v222 offset:23552
	global_load_lds_dwordx4 v[238:239], off
	v_lshl_add_u64 v[240:241], v[238:239], 0, s[40:41]
	s_add_i32 m0, s33, 0x2000
	s_add_i32 s33, s87, s14
	global_load_lds_dwordx4 v[240:241], off
	v_lshl_add_u64 v[240:241], v[238:239], 0, s[42:43]
	s_mov_b32 m0, s33
	s_nop 0
	global_load_lds_dwordx4 v[240:241], off
	v_lshl_add_u64 v[240:241], v[238:239], 0, s[44:45]
	s_add_i32 m0, s33, 0x2000
	s_nop 0
	global_load_lds_dwordx4 v[240:241], off
	v_lshl_add_u64 v[240:241], s[74:75], 0, v[190:191]
	s_mov_b32 m0, s15
	v_lshl_add_u64 v[242:243], v[240:241], 0, s[40:41]
	global_load_lds_dwordx4 v[240:241], off
	s_mov_b32 m0, s17
	s_nop 0
	global_load_lds_dwordx4 v[242:243], off
	s_waitcnt vmcnt(8)
	s_waitcnt lgkmcnt(0)
	s_barrier
; #define PG8_STAGE(bufoff, gbase, voff) do { _Pragma("unroll") for (int _i = 0; _i < 2; ++_i) \
;         __builtin_amdgcn_global_load_lds((const unsigned*)((const char*)(gbase) + (voff)[_i]), (PG8_LAS unsigned*)(lds + (bufoff) + ldsw + _i * 8192), 16, 0, 0); } while (0)
; #define PG8_LDA(dst, b, h) do { _Pragma("unroll") for (int m = 0; m < 4; ++m) _Pragma("unroll") for (int k = 0; k < 2; ++k) dst[m][k] = *(const PG8_LAS bf16x8*)(lds + PG8_SA(b, h) + aoff + m * 2048 + k * 1024); } while (0)
; #define PG8_LDB(dst, b, h) do { _Pragma("unroll") for (int n = 0; n < 2; ++n) _Pragma("unroll") for (int k = 0; k < 2; ++k) dst[n][k] = *(const PG8_LAS bf16x8*)(lds + PG8_SB(b, h) + boff + n * 2048 + k * 1024); } while (0)
; #define PG8_MMA(ai, bj, At, Bt) do { __builtin_amdgcn_s_setprio(1); _Pragma("unroll") for (int m = 0; m < 4; ++m) _Pragma("unroll") for (int n = 0; n < 2; ++n) _Pragma("unroll") for (int k = 0; k < 2; ++k) \
;         acc[ai][bj][m][n] = __builtin_amdgcn_mfma_f32_16x16x32_bf16(Bt[n][k], At[m][k], acc[ai][bj][m][n], 0, 0, 0); __builtin_amdgcn_s_setprio(0); } while (0)
; #define PG8_WAIT_V(n) asm volatile("s_waitcnt vmcnt(" #n ")" ::: "memory")
; #define PG8_WAIT_L(n) asm volatile("s_waitcnt lgkmcnt(" #n ")" ::: "memory")
; #define PG8_BAR __builtin_amdgcn_s_barrier()
; #define PG8_SCHED __builtin_amdgcn_sched_barrier(0)
; template <class Epi, class Sched, bool ALIGN_EPI = false, bool SP2 = false>
; __device__ __forceinline__ void gemm_phase(PG8_LAS unsigned char* lds, const Gemm g, const Sched& S, const Epi& E) {
;     ...
;             PG8_WAIT_V(8); PG8_WAIT_L(0); PG8_BAR; PG8_MMA(1, 0, At, B0); PG8_MMA(1, 1, At, B1); PG8_BAR; PG8_SCHED;
;             PG8_LDB(B0, 1, 0); PG8_LDB(B1, 1, 1); PG8_SCHED; PG8_LDA(At, 1, 0); PG8_STAGE(PG8_SA(0, 1), a2 + hstepA, voffA);
;             PG8_WAIT_V(8); PG8_WAIT_L(0); PG8_BAR; PG8_MMA(0, 0, At, B0); PG8_MMA(0, 1, At, B1); PG8_BAR; PG8_SCHED;
	s_waitcnt lgkmcnt(0)
	v_mfma_f32_16x16x32_bf16 v[60:63], v[128:131], v[160:163], v[60:63]
	v_mfma_f32_16x16x32_bf16 v[56:59], v[136:139], v[160:163], v[56:59]
	v_mfma_f32_16x16x32_bf16 v[44:47], v[128:131], v[168:171], v[44:47]
	v_mfma_f32_16x16x32_bf16 v[40:43], v[136:139], v[168:171], v[40:43]
	v_mfma_f32_16x16x32_bf16 v[28:31], v[128:131], v[176:179], v[28:31]
	v_mfma_f32_16x16x32_bf16 v[24:27], v[136:139], v[176:179], v[24:27]
	v_mfma_f32_16x16x32_bf16 v[12:15], v[128:131], v[230:233], v[12:15]
	v_mfma_f32_16x16x32_bf16 v[8:11], v[136:139], v[230:233], v[8:11]
	v_mfma_f32_16x16x32_bf16 v[60:63], v[132:135], v[164:167], v[60:63]
	v_mfma_f32_16x16x32_bf16 v[56:59], v[140:143], v[164:167], v[56:59]
	v_mfma_f32_16x16x32_bf16 v[44:47], v[132:135], v[172:175], v[44:47]
	v_mfma_f32_16x16x32_bf16 v[40:43], v[140:143], v[172:175], v[40:43]
	v_mfma_f32_16x16x32_bf16 v[28:31], v[132:135], v[180:183], v[28:31]
	v_mfma_f32_16x16x32_bf16 v[24:27], v[140:143], v[180:183], v[24:27]
	v_mfma_f32_16x16x32_bf16 v[12:15], v[132:135], v[234:237], v[12:15]
	v_mfma_f32_16x16x32_bf16 v[8:11], v[140:143], v[234:237], v[8:11]
	v_mfma_f32_16x16x32_bf16 v[52:55], v[144:147], v[160:163], v[52:55]
	v_mfma_f32_16x16x32_bf16 v[48:51], v[152:155], v[160:163], v[48:51]
	v_mfma_f32_16x16x32_bf16 v[36:39], v[144:147], v[168:171], v[36:39]
	v_mfma_f32_16x16x32_bf16 v[32:35], v[152:155], v[168:171], v[32:35]
	v_mfma_f32_16x16x32_bf16 v[20:23], v[144:147], v[176:179], v[20:23]
	v_mfma_f32_16x16x32_bf16 v[16:19], v[152:155], v[176:179], v[16:19]
	v_mfma_f32_16x16x32_bf16 v[4:7], v[144:147], v[230:233], v[4:7]
	v_mfma_f32_16x16x32_bf16 v[0:3], v[152:155], v[230:233], v[0:3]
	v_mfma_f32_16x16x32_bf16 v[52:55], v[148:151], v[164:167], v[52:55]
	v_mfma_f32_16x16x32_bf16 v[48:51], v[156:159], v[164:167], v[48:51]
	v_mfma_f32_16x16x32_bf16 v[36:39], v[148:151], v[172:175], v[36:39]
	v_mfma_f32_16x16x32_bf16 v[32:35], v[156:159], v[172:175], v[32:35]
	v_mfma_f32_16x16x32_bf16 v[20:23], v[148:151], v[180:183], v[20:23]
	v_mfma_f32_16x16x32_bf16 v[16:19], v[156:159], v[180:183], v[16:19]
	v_mfma_f32_16x16x32_bf16 v[4:7], v[148:151], v[234:237], v[4:7]
	v_mfma_f32_16x16x32_bf16 v[0:3], v[156:159], v[234:237], v[0:3]
	s_barrier
	ds_read_b128 v[128:131], v223
	ds_read_b128 v[132:135], v223 offset:1024
	ds_read_b128 v[136:139], v223 offset:2048
	ds_read_b128 v[140:143], v223 offset:3072
	ds_read_b128 v[144:147], v224
	ds_read_b128 v[148:151], v224 offset:1024
	ds_read_b128 v[152:155], v224 offset:2048
	ds_read_b128 v[156:159], v224 offset:3072
	s_mov_b32 m0, s18
	v_lshl_add_u64 v[242:243], v[240:241], 0, s[42:43]
	ds_read_b128 v[160:163], v222 offset:32768
	ds_read_b128 v[164:167], v222 offset:33792
	ds_read_b128 v[168:171], v222 offset:34816
	ds_read_b128 v[172:175], v222 offset:35840
	ds_read_b128 v[176:179], v222 offset:36864
	ds_read_b128 v[180:183], v222 offset:37888
	ds_read_b128 v[230:233], v222 offset:38912
	ds_read_b128 v[234:237], v222 offset:39936
	global_load_lds_dwordx4 v[242:243], off
	v_lshl_add_u64 v[242:243], v[240:241], 0, s[44:45]
	s_mov_b32 m0, s19
	s_nop 0
	global_load_lds_dwordx4 v[242:243], off
	s_waitcnt vmcnt(8)
	s_waitcnt lgkmcnt(0)
	s_barrier
	s_waitcnt lgkmcnt(0)
	v_mfma_f32_16x16x32_bf16 v[124:127], v[128:131], v[160:163], v[124:127]
	v_mfma_f32_16x16x32_bf16 v[120:123], v[136:139], v[160:163], v[120:123]
	v_mfma_f32_16x16x32_bf16 v[108:111], v[128:131], v[168:171], v[108:111]
	v_mfma_f32_16x16x32_bf16 v[104:107], v[136:139], v[168:171], v[104:107]
	v_mfma_f32_16x16x32_bf16 v[92:95], v[128:131], v[176:179], v[92:95]
	v_mfma_f32_16x16x32_bf16 v[88:91], v[136:139], v[176:179], v[88:91]
	v_mfma_f32_16x16x32_bf16 v[76:79], v[128:131], v[230:233], v[76:79]
	v_mfma_f32_16x16x32_bf16 v[72:75], v[136:139], v[230:233], v[72:75]
	v_mfma_f32_16x16x32_bf16 v[124:127], v[132:135], v[164:167], v[124:127]
	v_mfma_f32_16x16x32_bf16 v[120:123], v[140:143], v[164:167], v[120:123]
	v_mfma_f32_16x16x32_bf16 v[108:111], v[132:135], v[172:175], v[108:111]
	v_mfma_f32_16x16x32_bf16 v[104:107], v[140:143], v[172:175], v[104:107]
	v_mfma_f32_16x16x32_bf16 v[92:95], v[132:135], v[180:183], v[92:95]
	v_mfma_f32_16x16x32_bf16 v[88:91], v[140:143], v[180:183], v[88:91]
	v_mfma_f32_16x16x32_bf16 v[76:79], v[132:135], v[234:237], v[76:79]
	v_mfma_f32_16x16x32_bf16 v[72:75], v[140:143], v[234:237], v[72:75]
	v_mfma_f32_16x16x32_bf16 v[116:119], v[144:147], v[160:163], v[116:119]
	v_mfma_f32_16x16x32_bf16 v[112:115], v[152:155], v[160:163], v[112:115]
	v_mfma_f32_16x16x32_bf16 v[100:103], v[144:147], v[168:171], v[100:103]
	v_mfma_f32_16x16x32_bf16 v[96:99], v[152:155], v[168:171], v[96:99]
	v_mfma_f32_16x16x32_bf16 v[84:87], v[144:147], v[176:179], v[84:87]
	v_mfma_f32_16x16x32_bf16 v[80:83], v[152:155], v[176:179], v[80:83]
	v_mfma_f32_16x16x32_bf16 v[68:71], v[144:147], v[230:233], v[68:71]
	v_mfma_f32_16x16x32_bf16 v[64:67], v[152:155], v[230:233], v[64:67]
	v_mfma_f32_16x16x32_bf16 v[116:119], v[148:151], v[164:167], v[116:119]
	v_mfma_f32_16x16x32_bf16 v[112:115], v[156:159], v[164:167], v[112:115]
	v_mfma_f32_16x16x32_bf16 v[100:103], v[148:151], v[172:175], v[100:103]
	v_mfma_f32_16x16x32_bf16 v[96:99], v[156:159], v[172:175], v[96:99]
	v_mfma_f32_16x16x32_bf16 v[84:87], v[148:151], v[180:183], v[84:87]
	v_mfma_f32_16x16x32_bf16 v[80:83], v[156:159], v[180:183], v[80:83]
	v_mfma_f32_16x16x32_bf16 v[68:71], v[148:151], v[234:237], v[68:71]
	v_mfma_f32_16x16x32_bf16 v[64:67], v[156:159], v[234:237], v[64:67]
	s_barrier
; #define PG8_STAGE(bufoff, gbase, voff) do { _Pragma("unroll") for (int _i = 0; _i < 2; ++_i) \
;         __builtin_amdgcn_global_load_lds((const unsigned*)((const char*)(gbase) + (voff)[_i]), (PG8_LAS unsigned*)(lds + (bufoff) + ldsw + _i * 8192), 16, 0, 0); } while (0)
; #define PG8_LDA(dst, b, h) do { _Pragma("unroll") for (int m = 0; m < 4; ++m) _Pragma("unroll") for (int k = 0; k < 2; ++k) dst[m][k] = *(const PG8_LAS bf16x8*)(lds + PG8_SA(b, h) + aoff + m * 2048 + k * 1024); } while (0)
; #define PG8_MMA(ai, bj, At, Bt) do { __builtin_amdgcn_s_setprio(1); _Pragma("unroll") for (int m = 0; m < 4; ++m) _Pragma("unroll") for (int n = 0; n < 2; ++n) _Pragma("unroll") for (int k = 0; k < 2; ++k) \
;         acc[ai][bj][m][n] = __builtin_amdgcn_mfma_f32_16x16x32_bf16(Bt[n][k], At[m][k], acc[ai][bj][m][n], 0, 0, 0); __builtin_amdgcn_s_setprio(0); } while (0)
; #define PG8_WAIT_V(n) asm volatile("s_waitcnt vmcnt(" #n ")" ::: "memory")
; #define PG8_WAIT_L(n) asm volatile("s_waitcnt lgkmcnt(" #n ")" ::: "memory")
; #define PG8_BAR __builtin_amdgcn_s_barrier()
; #define PG8_SCHED __builtin_amdgcn_sched_barrier(0)
; template <class Epi, class Sched, bool ALIGN_EPI = false, bool SP2 = false>
; __device__ __forceinline__ void gemm_phase(PG8_LAS unsigned char* lds, const Gemm g, const Sched& S, const Epi& E) {
;     ...
;             PG8_LDA(At, 1, 1); PG8_STAGE(PG8_SB(1, 0), b3, voffB); PG8_STAGE(PG8_SB(1, 1), b3 + hstepB, voffB); PG8_STAGE(PG8_SA(1, 0), a3, voffA);
;             PG8_WAIT_V(8); PG8_WAIT_L(0); PG8_BAR; PG8_MMA(1, 0, At, B0); PG8_MMA(1, 1, At, B1); PG8_BAR; PG8_SCHED;
;     ...
;         if constexpr (ALIGN_EPI) { if (wr == 0) PG8_BAR; }
	s_add_i32 s33, s88, s14
	v_lshl_add_u64 v[242:243], v[238:239], 0, s[46:47]
	s_mov_b32 m0, s33
	ds_read_b128 v[160:163], v222 offset:49152
	ds_read_b128 v[164:167], v222 offset:50176
	ds_read_b128 v[168:171], v222 offset:51200
	ds_read_b128 v[172:175], v222 offset:52224
	ds_read_b128 v[176:179], v222 offset:53248
	ds_read_b128 v[180:183], v222 offset:54272
	ds_read_b128 v[230:233], v222 offset:55296
	ds_read_b128 v[234:237], v222 offset:56320
	global_load_lds_dwordx4 v[242:243], off
	v_lshl_add_u64 v[242:243], v[238:239], 0, s[48:49]
	s_add_i32 m0, s33, 0x2000
	s_add_i32 s33, s89, s14
	global_load_lds_dwordx4 v[242:243], off
	v_lshl_add_u64 v[242:243], v[238:239], 0, s[52:53]
	s_mov_b32 m0, s33
	v_lshl_add_u64 v[238:239], v[238:239], 0, s[54:55]
	global_load_lds_dwordx4 v[242:243], off
	s_add_i32 m0, s33, 0x2000
	s_nop 0
	global_load_lds_dwordx4 v[238:239], off
	v_lshl_add_u64 v[238:239], v[240:241], 0, s[46:47]
	s_mov_b32 m0, s80
	s_nop 0
	global_load_lds_dwordx4 v[238:239], off
	v_lshl_add_u64 v[238:239], v[240:241], 0, s[48:49]
	s_mov_b32 m0, s81
	s_nop 0
	global_load_lds_dwordx4 v[238:239], off
	s_waitcnt vmcnt(8)
	s_waitcnt lgkmcnt(0)
	s_barrier
	s_waitcnt lgkmcnt(0)
	v_mfma_f32_16x16x32_bf16 v[60:63], v[128:131], v[160:163], v[60:63]
	v_mfma_f32_16x16x32_bf16 v[56:59], v[136:139], v[160:163], v[56:59]
	v_mfma_f32_16x16x32_bf16 v[44:47], v[128:131], v[168:171], v[44:47]
	v_mfma_f32_16x16x32_bf16 v[40:43], v[136:139], v[168:171], v[40:43]
	v_mfma_f32_16x16x32_bf16 v[28:31], v[128:131], v[176:179], v[28:31]
	v_mfma_f32_16x16x32_bf16 v[24:27], v[136:139], v[176:179], v[24:27]
	v_mfma_f32_16x16x32_bf16 v[12:15], v[128:131], v[230:233], v[12:15]
	v_mfma_f32_16x16x32_bf16 v[8:11], v[136:139], v[230:233], v[8:11]
	v_mfma_f32_16x16x32_bf16 v[60:63], v[132:135], v[164:167], v[60:63]
	v_mfma_f32_16x16x32_bf16 v[56:59], v[140:143], v[164:167], v[56:59]
	v_mfma_f32_16x16x32_bf16 v[44:47], v[132:135], v[172:175], v[44:47]
	v_mfma_f32_16x16x32_bf16 v[40:43], v[140:143], v[172:175], v[40:43]
	v_mfma_f32_16x16x32_bf16 v[28:31], v[132:135], v[180:183], v[28:31]
	v_mfma_f32_16x16x32_bf16 v[24:27], v[140:143], v[180:183], v[24:27]
	v_mfma_f32_16x16x32_bf16 v[12:15], v[132:135], v[234:237], v[12:15]
	v_mfma_f32_16x16x32_bf16 v[8:11], v[140:143], v[234:237], v[8:11]
	v_mfma_f32_16x16x32_bf16 v[52:55], v[144:147], v[160:163], v[52:55]
	v_mfma_f32_16x16x32_bf16 v[48:51], v[152:155], v[160:163], v[48:51]
	v_mfma_f32_16x16x32_bf16 v[36:39], v[144:147], v[168:171], v[36:39]
	v_mfma_f32_16x16x32_bf16 v[32:35], v[152:155], v[168:171], v[32:35]
	v_mfma_f32_16x16x32_bf16 v[20:23], v[144:147], v[176:179], v[20:23]
	v_mfma_f32_16x16x32_bf16 v[16:19], v[152:155], v[176:179], v[16:19]
	v_mfma_f32_16x16x32_bf16 v[4:7], v[144:147], v[230:233], v[4:7]
	v_mfma_f32_16x16x32_bf16 v[0:3], v[152:155], v[230:233], v[0:3]
	v_mfma_f32_16x16x32_bf16 v[52:55], v[148:151], v[164:167], v[52:55]
	v_mfma_f32_16x16x32_bf16 v[48:51], v[156:159], v[164:167], v[48:51]
	v_mfma_f32_16x16x32_bf16 v[36:39], v[148:151], v[172:175], v[36:39]
	v_mfma_f32_16x16x32_bf16 v[32:35], v[156:159], v[172:175], v[32:35]
	v_mfma_f32_16x16x32_bf16 v[20:23], v[148:151], v[180:183], v[20:23]
	v_mfma_f32_16x16x32_bf16 v[16:19], v[156:159], v[180:183], v[16:19]
	v_mfma_f32_16x16x32_bf16 v[4:7], v[148:151], v[234:237], v[4:7]
	v_mfma_f32_16x16x32_bf16 v[0:3], v[156:159], v[234:237], v[0:3]
	s_barrier
	s_add_i32 s73, s73, 2
	s_add_u32 s70, s70, 0x10000
	s_addc_u32 s71, s71, 0
	s_add_u32 s69, s69, 0x10000
	s_addc_u32 s72, s72, 0
	s_cmp_gt_u32 s73, 41
	s_cbranch_scc0 .LBB0_1004
	s_and_b64 vcc, exec, s[60:61]
	s_cbranch_vccz .LBB0_1007
	s_barrier

; __global__ void __launch_bounds__(NTHR, 2) mk_fwd(Args args) {
	.amdhsa_kernel _Z6mk_fwd4Args
		.amdhsa_group_segment_fixed_size 0
		.amdhsa_private_segment_fixed_size 0
		.amdhsa_kernarg_size 408
		.amdhsa_user_sgpr_count 2
		.amdhsa_user_sgpr_dispatch_ptr 0
		.amdhsa_user_sgpr_queue_ptr 0
		.amdhsa_user_sgpr_kernarg_segment_ptr 1
		.amdhsa_user_sgpr_dispatch_id 0
		.amdhsa_user_sgpr_kernarg_preload_length 0
		.amdhsa_user_sgpr_kernarg_preload_offset 0
		.amdhsa_user_sgpr_private_segment_size 0
		.amdhsa_uses_dynamic_stack 0
		.amdhsa_enable_private_segment 0
		.amdhsa_system_sgpr_workgroup_id_x 1
		.amdhsa_system_sgpr_workgroup_id_y 0
		.amdhsa_system_sgpr_workgroup_id_z 0
		.amdhsa_system_sgpr_workgroup_info 0
		.amdhsa_system_vgpr_workitem_id 2
		.amdhsa_next_free_vgpr 250
		.amdhsa_next_free_sgpr 102
		.amdhsa_accum_offset 252
		.amdhsa_reserve_vcc 1
		.amdhsa_float_round_mode_32 0
		.amdhsa_float_round_mode_16_64 0
		.amdhsa_float_denorm_mode_32 3
		.amdhsa_float_denorm_mode_16_64 3
		.amdhsa_dx10_clamp 1
		.amdhsa_ieee_mode 1
		.amdhsa_fp16_overflow 0
		.amdhsa_tg_split 0
		.amdhsa_exception_fp_ieee_invalid_op 0
		.amdhsa_exception_fp_denorm_src 0
		.amdhsa_exception_fp_ieee_div_zero 0
		.amdhsa_exception_fp_ieee_overflow 0
		.amdhsa_exception_fp_ieee_underflow 0
		.amdhsa_exception_fp_ieee_inexact 0
		.amdhsa_exception_int_div_zero 0
	.end_amdhsa_kernel

; __global__ void __launch_bounds__(NTHR, 2) mk_fwd(Args args) {
amdhsa.kernels:
  - .agpr_count:     0
    .args:
      - .offset:         0
        .size:           152
        .value_kind:     by_value
      - .offset:         152
        .size:           4
        .value_kind:     hidden_block_count_x
      - .offset:         156
        .size:           4
        .value_kind:     hidden_block_count_y
      - .offset:         160
        .size:           4
        .value_kind:     hidden_block_count_z
      - .offset:         164
        .size:           2
        .value_kind:     hidden_group_size_x
      - .offset:         166
        .size:           2
        .value_kind:     hidden_group_size_y
      - .offset:         168
        .size:           2
        .value_kind:     hidden_group_size_z
      - .offset:         170
        .size:           2
        .value_kind:     hidden_remainder_x
      - .offset:         172
        .size:           2
        .value_kind:     hidden_remainder_y
      - .offset:         174
        .size:           2
        .value_kind:     hidden_remainder_z
      - .offset:         192
        .size:           8
        .value_kind:     hidden_global_offset_x
      - .offset:         200
        .size:           8
        .value_kind:     hidden_global_offset_y
      - .offset:         208
        .size:           8
        .value_kind:     hidden_global_offset_z
      - .offset:         216
        .size:           2
        .value_kind:     hidden_grid_dims
      - .offset:         240
        .size:           8
        .value_kind:     hidden_multigrid_sync_arg
      - .offset:         272
        .size:           4
        .value_kind:     hidden_dynamic_lds_size
    .group_segment_fixed_size: 0
    .kernarg_segment_align: 8
    .kernarg_segment_size: 408
    .language:       OpenCL C
    .language_version:
      - 2
      - 0
    .max_flat_workgroup_size: 512
    .name:           _Z6mk_fwd4Args
    .private_segment_fixed_size: 0
    .sgpr_count:     108
    .sgpr_spill_count: 12
    .symbol:         _Z6mk_fwd4Args.kd
    .uniform_work_group_size: 1
    .uses_dynamic_stack: false
    .vgpr_count:     250
    .vgpr_spill_count: 0
    .wavefront_size: 64
